# chunk scan moved into phase 3 on idle workgroups 192..255 (ProbS completion counter + L2 writeback release), phase-4 grid barrier removed
# speedup vs baseline: 1.0483x; 1.0007x over previous
.LBB0_348:
	s_barrier
	s_and_saveexec_b64 s[98:99], s[96:97]
	s_cbranch_execz .Lps_sig_done
	buffer_wbl2 sc1
	s_waitcnt vmcnt(0)
	v_mov_b32_e32 v242, 0x2ee0
	v_mov_b32_e32 v243, 1
	v_readlane_b32 s100, v241, 10
	v_readlane_b32 s101, v241, 11
	s_nop 4
	global_atomic_add v242, v243, s[100:101]
.Lps_sig_done:
	s_or_b64 exec, exec, s[98:99]

.LBB0_404:
	s_waitcnt vmcnt(0)
	s_waitcnt vmcnt(0) lgkmcnt(0)
	s_barrier
	s_cmpk_lt_i32 s81, 0xc0
	s_cbranch_scc1 .Lgs4_start
	v_mov_b32_e32 v242, 0x2ee0
	v_readlane_b32 s100, v241, 10
	v_readlane_b32 s101, v241, 11
	s_mov_b32 s99, 0
	s_nop 4
.Lscan_spin:
	global_load_dword v243, v242, s[100:101] sc1
	s_waitcnt vmcnt(0)
	v_readfirstlane_b32 s98, v243
	s_cmpk_ge_u32 s98, 0xc0
	s_cbranch_scc1 .Lscan_go
	s_sleep 4
	s_add_i32 s99, s99, 1
	s_cmp_lt_u32 s99, 0x20000
	s_cbranch_scc1 .Lscan_spin
.Lscan_go:
	buffer_inv sc1
	s_waitcnt vmcnt(0)
	v_mov_b32_e32 v3, 0
	v_readlane_b32 s8, v241, 0
	v_lshlrev_b32_e32 v0, 1, v192
	v_mov_b32_e32 v1, v3
	v_readlane_b32 s10, v241, 2
	v_readlane_b32 s11, v241, 3
	v_readlane_b32 s16, v241, 8
	v_readlane_b32 s17, v241, 9
	s_movk_i32 s2, 0x220
	s_movk_i32 s3, 0x200
	v_lshl_add_u64 v[4:5], s[16:17], 0, v[0:1]
	v_lshlrev_b32_e32 v6, 1, v192
	v_mov_b32_e32 v7, v3
	s_movk_i32 s10, 0x7fff
	s_sub_i32 s11, s81, 0xc0
	v_readlane_b32 s9, v241, 1
	v_readlane_b32 s12, v241, 4
	v_readlane_b32 s13, v241, 5
	v_readlane_b32 s14, v241, 6
	v_readlane_b32 s15, v241, 7
	v_readlane_b32 s18, v241, 10
	v_readlane_b32 s19, v241, 11
	v_readlane_b32 s20, v241, 12
	v_readlane_b32 s21, v241, 13
	v_readlane_b32 s22, v241, 14
	v_readlane_b32 s23, v241, 15
	s_branch .LBB0_459
.LBB0_458:
	s_add_i32 s11, s11, 64
	s_cmpk_gt_i32 s11, 0x7f
	s_cbranch_scc1 .LBB0_495

.Lgs4_start:
	s_and_saveexec_b64 s[0:1], s[96:97]
	s_cbranch_execz .LBB0_456
	s_add_i32 s2, 0, 0x20010
	v_mov_b32_e32 v0, s2
	s_waitcnt vmcnt(0) expcnt(0) lgkmcnt(0)
	ds_read_b32 v2, v0
	s_add_i32 s2, 0, 0x20014
	v_mov_b32_e32 v0, s2
	ds_read_b32 v0, v0
	s_waitcnt lgkmcnt(1)
	v_cmp_ne_u32_e32 vcc, 0, v2
	s_cbranch_vccnz .LBB0_420
	v_readlane_b32 s8, v241, 0
	v_readlane_b32 s20, v241, 12
	v_readlane_b32 s21, v241, 13
	s_add_u32 s4, s20, 0x1000
	v_readlane_b32 s14, v241, 6
	s_addc_u32 s5, s21, 0
	v_readlane_b32 s15, v241, 7
	s_add_u32 s14, s20, 0x1100
	s_addc_u32 s15, s21, 0
	s_add_u32 s30, s20, 0x1200
	v_readlane_b32 s2, v241, 16
	s_addc_u32 s31, s21, 0
	s_mul_i32 s2, s83, s2
	s_add_u32 s36, s20, 0x1300
	s_mul_i32 s2, s2, s82
	s_addc_u32 s37, s21, 0
	s_mov_b32 s3, 1
	v_mov_b32_e32 v16, 0
	v_readlane_b32 s9, v241, 1
	v_readlane_b32 s10, v241, 2
	v_readlane_b32 s11, v241, 3
	v_readlane_b32 s12, v241, 4
	v_readlane_b32 s13, v241, 5
	v_readlane_b32 s16, v241, 8
	v_readlane_b32 s17, v241, 9
	v_readlane_b32 s18, v241, 10
	v_readlane_b32 s19, v241, 11
	v_readlane_b32 s22, v241, 14
	v_readlane_b32 s23, v241, 15
	s_branch .LBB0_408

.LBB0_455:
	s_or_b64 exec, exec, s[30:31]
	s_waitcnt vmcnt(0)
.LBB0_456:
	s_or_b64 exec, exec, s[0:1]
	v_mov_b32_e32 v4, v193
	s_waitcnt lgkmcnt(0)
	s_barrier
	s_and_b64 vcc, exec, s[88:89]
	v_readfirstlane_b32 s2, v4
	s_cbranch_vccz .LBB0_550
	s_mov_b64 s[4:5], 0
	s_cmpk_gt_i32 s81, 0x1ff
	s_mov_b64 s[0:1], 0
	s_cbranch_scc1 .LBB0_551
	s_and_b32 s68, s81, 3
	s_bfe_u32 s69, s81, 0x10002
	s_ashr_i32 s22, s81, 3
	s_mov_b64 s[0:1], -1
	s_branch .LBB0_551
